# PEER U pass counting sort: 64-lane prefix sums by DPP row shifts and row broadcasts instead of six ds_bpermute rounds
# speedup vs baseline: 1.0022x; 1.0022x over previous
; DI float bflo(unsigned u) { return __uint_as_float(u << 16); }
; DI float bfhi(unsigned u) { return __uint_as_float(u & 0xffff0000u); }
; template <bool STORE>
; DI void peer_item(const Params& p, int item, char* smem) {
;     ...
;   const unsigned char* U8 = (const unsigned char*)(ws + WS_UBF);
;   const float* SU = (const float*)(ws + WS_SU);
;   const float* SV = (const float*)(ws + WS_SV);
;   int* EG = (int*)(ws + WS_XN);
;   float* AG = (float*)(ws + WS_XN + (size_t)T_TOK * 128 * 4);
;   const bool b5 = (lane & 32) != 0, b4 = (lane & 16) != 0, b3 = (lane & 8) != 0;
; #pragma unroll 1
;   for (int ti = 0; ti < 8; ++ti) {
;     const int tl = wave * 8 + ti;
;     const size_t tok = (size_t)tok0 + tl;
;     float xf[16];
;     {
; #pragma unroll
;       for (int i = 0; i < 4; ++i) {
;         const uint2 xv = *(const uint2*)(XN2 + tok * 1024 + 256 * i + lane * 4);
;         xf[4 * i] = bflo(xv.x); xf[4 * i + 1] = bfhi(xv.x); xf[4 * i + 2] = bflo(xv.y); xf[4 * i + 3] = bfhi(xv.y);
;       }
;     }
.LBB0_1058:
	s_or_b64 exec, exec, s[0:1]
	s_waitcnt vmcnt(0) lgkmcnt(0)
	v_writelane_b32 v254, s6, 0
	v_writelane_b32 v254, s7, 1
	v_writelane_b32 v254, s12, 2
	v_writelane_b32 v254, s13, 3
	v_writelane_b32 v254, s14, 4
	v_writelane_b32 v254, s15, 5
	v_writelane_b32 v254, s16, 6
	v_writelane_b32 v254, s17, 7
	v_writelane_b32 v254, s18, 8
	v_writelane_b32 v254, s19, 9
	v_writelane_b32 v254, s20, 10
	v_writelane_b32 v254, s21, 11
	v_writelane_b32 v254, s22, 12
	v_writelane_b32 v254, s23, 13
	v_writelane_b32 v254, s24, 14
	v_writelane_b32 v254, s25, 15
	v_writelane_b32 v254, s26, 16
	v_writelane_b32 v254, s27, 17
	v_writelane_b32 v254, s28, 18
	v_writelane_b32 v254, s29, 19
	v_writelane_b32 v254, s30, 20
	v_writelane_b32 v254, s31, 21
	v_writelane_b32 v254, s33, 22
	v_writelane_b32 v254, s34, 23
	v_writelane_b32 v254, s35, 24
	v_writelane_b32 v254, s36, 25
	v_writelane_b32 v254, s37, 26
	v_writelane_b32 v254, s38, 27
	v_writelane_b32 v254, s39, 28
	v_writelane_b32 v254, s40, 29
	v_writelane_b32 v254, s41, 30
	v_writelane_b32 v254, s42, 31
	v_writelane_b32 v254, s44, 32
	v_writelane_b32 v254, s45, 33
	v_writelane_b32 v254, s48, 34
	v_writelane_b32 v254, s49, 35
	v_writelane_b32 v254, s50, 36
	v_writelane_b32 v254, s51, 37
	v_writelane_b32 v254, s52, 38
	v_writelane_b32 v254, s53, 39
	v_writelane_b32 v254, s55, 40
	v_writelane_b32 v254, s60, 41
	v_writelane_b32 v254, s61, 42
	v_writelane_b32 v254, s62, 43
	v_writelane_b32 v254, s63, 44
	v_writelane_b32 v254, s66, 45
	v_writelane_b32 v254, s67, 46
	v_writelane_b32 v254, s68, 47
	v_writelane_b32 v254, s69, 48
	v_writelane_b32 v254, s74, 49
	v_writelane_b32 v254, s75, 50
	v_writelane_b32 v254, s76, 51
	v_writelane_b32 v254, s77, 52
	v_writelane_b32 v254, s78, 53
	v_writelane_b32 v254, s79, 54
	v_writelane_b32 v254, s88, 55
	s_mov_b32 s16, s33
	s_mov_b32 s14, s42
	v_readlane_b32 s56, v253, 48
	v_readlane_b32 s57, v253, 49
	v_readfirstlane_b32 s13, v211
	v_mbcnt_lo_u32_b32 v213, -1, 0
	v_mbcnt_hi_u32_b32 v213, -1, v213
	s_nop 3
	s_bfe_u32 s17, s13, 0x20006
	s_add_u32 s0, s56, 0x1200200
	s_addc_u32 s1, s57, 0
	s_add_u32 s2, s56, 0x7200200
	s_addc_u32 s3, s57, 0
	s_add_u32 s4, s56, 0x5200200
	s_addc_u32 s5, s57, 0
	s_add_u32 s6, s56, 0x5a00200
	s_addc_u32 s7, s57, 0
	s_add_u32 s8, s56, 0x2200200
	s_addc_u32 s9, s57, 0
	s_add_u32 s10, s56, 0x4200200
	s_addc_u32 s11, s57, 0
	s_lshl_b32 s13, s17, 3
	s_add_u32 s14, s14, s13
	s_mul_i32 s18, s17, 7680
	s_add_u32 s18, s18, s16
	s_add_u32 s18, s18, 49152
	s_lshl_b32 s19, s17, 12
	s_add_u32 s19, s19, s16
	v_lshlrev_b32_e32 v238, 2, v213
	v_lshlrev_b32_e32 v234, 4, v213
	v_add_u32_e32 v236, s18, v238
	v_add_u32_e32 v237, s19, v238
	ds_write_b32 v236, v3 offset:512
	ds_write_b32 v236, v53 offset:768
	ds_write_b32 v236, v64 offset:1024
	ds_write_b32 v236, v65 offset:1280
	ds_write_b32 v236, v66 offset:1536
	ds_write_b32 v236, v67 offset:1792
	ds_write_b32 v236, v68 offset:2048
	ds_write_b32 v236, v69 offset:2304
	ds_write_b32 v236, v70 offset:2560
	ds_write_b32 v236, v71 offset:2816
	ds_write_b32 v236, v72 offset:3072
	ds_write_b32 v236, v73 offset:3328
	ds_write_b32 v236, v74 offset:3584
	ds_write_b32 v236, v75 offset:3840
	ds_write_b32 v236, v76 offset:4096
	ds_write_b32 v236, v77 offset:4352
	ds_write_b32 v236, v78 offset:4608
	ds_write_b32 v236, v79 offset:4864
	ds_write_b32 v236, v80 offset:5120
	ds_write_b32 v236, v81 offset:5376
	ds_write_b32 v236, v82 offset:5632
	ds_write_b32 v236, v83 offset:5888
	ds_write_b32 v236, v96 offset:6144
	ds_write_b32 v236, v210 offset:6400
	ds_write_b32 v236, v211 offset:6656
	ds_write_b32 v236, v212 offset:6912
	s_mov_b32 s24, 0xff00ff00
	s_mov_b32 s25, 0xff00ff00
	s_mov_b32 s80, 0x378e98ab
	s_mov_b32 s81, 0x3b7cd369
	s_mov_b32 s82, 0xbcc618b2
	s_mov_b32 s83, 0x3dda74e4
	s_mov_b32 s84, 0x3f228afd
	s_mov_b32 s85, 0x3e03c728
	s_mov_b32 s86, 0xbfb8aa3b
	s_mov_b32 s87, 0x42ce8ed0
	s_mov_b32 s88, 0xc2b17218
	s_mov_b32 s89, 0x7fffffff
	s_waitcnt lgkmcnt(0)
	s_lshl_b32 s13, s14, 11
	s_add_u32 s32, s2, s13
	s_addc_u32 s33, s3, 0
	v_lshlrev_b32_e32 v239, 3, v213
	s_add_u32 s34, s32, 0
	s_addc_u32 s35, s33, 0
	global_load_dwordx2 v[2:3], v239, s[34:35] offset:0
	global_load_dwordx2 v[6:7], v239, s[34:35] offset:512
	global_load_dwordx2 v[10:11], v239, s[34:35] offset:1024
	global_load_dwordx2 v[14:15], v239, s[34:35] offset:1536
	s_add_u32 s34, s32, 2048
	s_addc_u32 s35, s33, 0
	global_load_dwordx2 v[18:19], v239, s[34:35] offset:0
	global_load_dwordx2 v[22:23], v239, s[34:35] offset:512
	global_load_dwordx2 v[26:27], v239, s[34:35] offset:1024
	global_load_dwordx2 v[30:31], v239, s[34:35] offset:1536
	s_add_u32 s34, s32, 4096
	s_addc_u32 s35, s33, 0
	global_load_dwordx2 v[34:35], v239, s[34:35] offset:0
	global_load_dwordx2 v[38:39], v239, s[34:35] offset:512
	global_load_dwordx2 v[42:43], v239, s[34:35] offset:1024
	global_load_dwordx2 v[46:47], v239, s[34:35] offset:1536
	s_add_u32 s34, s32, 6144
	s_addc_u32 s35, s33, 0
	global_load_dwordx2 v[50:51], v239, s[34:35] offset:0
	global_load_dwordx2 v[54:55], v239, s[34:35] offset:512
	global_load_dwordx2 v[58:59], v239, s[34:35] offset:1024
	global_load_dwordx2 v[62:63], v239, s[34:35] offset:1536
	v_mov_b32_e32 v144, v236
	v_mov_b32_e32 v145, 0
	v_mov_b32_e32 v146, 1
	v_lshrrev_b32_e32 v147, 3, v213
	v_and_b32_e32 v148, 7, v213
	v_lshlrev_b32_e32 v147, 6, v147
	v_lshl_add_u32 v147, v148, 2, v147
	v_add_u32_e32 v147, s19, v147
	v_subrev_u32_e32 v149, 1, v213
	v_subrev_u32_e32 v150, 2, v213
	v_subrev_u32_e32 v151, 4, v213
	v_subrev_u32_e32 v152, 8, v213
	v_subrev_u32_e32 v153, 16, v213
	v_subrev_u32_e32 v154, 32, v213
	v_lshlrev_b32_e32 v149, 2, v149
	v_lshlrev_b32_e32 v150, 2, v150
	v_lshlrev_b32_e32 v151, 2, v151
	v_lshlrev_b32_e32 v152, 2, v152
	v_lshlrev_b32_e32 v153, 2, v153
	v_lshlrev_b32_e32 v154, 2, v154
	ds_read_b32 v166, v237 offset:0
	ds_read_b32 v167, v237 offset:256
	ds_read_b32 v168, v237 offset:16384
	ds_read_b32 v169, v237 offset:16640
	ds_write_b32 v144, v145 offset:0
	ds_write_b32 v144, v145 offset:256
	ds_read_b32 v180, v237 offset:512
	ds_read_b32 v181, v237 offset:768
	ds_read_b32 v182, v237 offset:16896
	ds_read_b32 v183, v237 offset:17152
	ds_write_b32 v144, v145 offset:7168
	ds_write_b32 v144, v145 offset:7424
	s_waitcnt lgkmcnt(0)
; template <bool STORE>
; DI void peer_item(const Params& p, int item, char* smem) {
;     ...
;     for (int k = 0; k < 128; k += 8) {
;       u32x4 uq[8];
;       const int emine = e_s[tl * 128 + k + (lane >> 3)];
;       const float gmine = g_s[tl * 128 + k + (lane >> 3)];
;       const float su = SU[emine], sv = SV[emine];
; #pragma unroll
;       for (int u = 0; u < 8; ++u) {
;         int e = e_s[tl * 128 + k + u];
;         uq[u] = *(const u32x4*)(U8 + (size_t)e * 1024 + lane * 16);
	v_lshrrev_b32_e32 v156, 5, v166
	v_and_b32_e32 v156, 0x1fc, v156
	v_add_u32_e32 v156, s18, v156
	v_lshrrev_b32_e32 v157, 5, v167
	v_and_b32_e32 v157, 0x1fc, v157
	v_add_u32_e32 v157, s18, v157
	v_lshrrev_b32_e32 v170, 5, v180
	v_and_b32_e32 v170, 0x1fc, v170
	v_add_u32_e32 v170, s18, v170
	v_add_u32_e32 v170, 7168, v170
	v_lshrrev_b32_e32 v171, 5, v181
	v_and_b32_e32 v171, 0x1fc, v171
	v_add_u32_e32 v171, s18, v171
	v_add_u32_e32 v171, 7168, v171
	ds_add_rtn_u32 v158, v156, v146
	ds_add_rtn_u32 v159, v157, v146
	ds_add_rtn_u32 v172, v170, v146
	ds_add_rtn_u32 v173, v171, v146
	ds_read_b32 v160, v144 offset:0
	ds_read_b32 v161, v144 offset:256
	ds_read_b32 v174, v144 offset:7168
	ds_read_b32 v175, v144 offset:7424
	s_waitcnt lgkmcnt(0)
	v_mov_b32_e32 v164, v160
	v_mov_b32_e32 v165, v161
	v_mov_b32_e32 v178, v174
	v_mov_b32_e32 v179, v175
	s_nop 1
	v_add_u32_dpp v164, v164, v164 row_shr:1 row_mask:0xf bank_mask:0xf bound_ctrl:0
	v_add_u32_dpp v165, v165, v165 row_shr:1 row_mask:0xf bank_mask:0xf bound_ctrl:0
	v_add_u32_dpp v178, v178, v178 row_shr:1 row_mask:0xf bank_mask:0xf bound_ctrl:0
	v_add_u32_dpp v179, v179, v179 row_shr:1 row_mask:0xf bank_mask:0xf bound_ctrl:0
	v_add_u32_dpp v164, v164, v164 row_shr:2 row_mask:0xf bank_mask:0xf bound_ctrl:0
	v_add_u32_dpp v165, v165, v165 row_shr:2 row_mask:0xf bank_mask:0xf bound_ctrl:0
	v_add_u32_dpp v178, v178, v178 row_shr:2 row_mask:0xf bank_mask:0xf bound_ctrl:0
	v_add_u32_dpp v179, v179, v179 row_shr:2 row_mask:0xf bank_mask:0xf bound_ctrl:0
	v_add_u32_dpp v164, v164, v164 row_shr:4 row_mask:0xf bank_mask:0xf bound_ctrl:0
	v_add_u32_dpp v165, v165, v165 row_shr:4 row_mask:0xf bank_mask:0xf bound_ctrl:0
	v_add_u32_dpp v178, v178, v178 row_shr:4 row_mask:0xf bank_mask:0xf bound_ctrl:0
	v_add_u32_dpp v179, v179, v179 row_shr:4 row_mask:0xf bank_mask:0xf bound_ctrl:0
	v_add_u32_dpp v164, v164, v164 row_shr:8 row_mask:0xf bank_mask:0xf bound_ctrl:0
	v_add_u32_dpp v165, v165, v165 row_shr:8 row_mask:0xf bank_mask:0xf bound_ctrl:0
	v_add_u32_dpp v178, v178, v178 row_shr:8 row_mask:0xf bank_mask:0xf bound_ctrl:0
	v_add_u32_dpp v179, v179, v179 row_shr:8 row_mask:0xf bank_mask:0xf bound_ctrl:0
	v_add_u32_dpp v164, v164, v164 row_bcast:15 row_mask:0xa bank_mask:0xf
	v_add_u32_dpp v165, v165, v165 row_bcast:15 row_mask:0xa bank_mask:0xf
	v_add_u32_dpp v178, v178, v178 row_bcast:15 row_mask:0xa bank_mask:0xf
	v_add_u32_dpp v179, v179, v179 row_bcast:15 row_mask:0xa bank_mask:0xf
	v_add_u32_dpp v164, v164, v164 row_bcast:31 row_mask:0xc bank_mask:0xf
	v_add_u32_dpp v165, v165, v165 row_bcast:31 row_mask:0xc bank_mask:0xf
	v_add_u32_dpp v178, v178, v178 row_bcast:31 row_mask:0xc bank_mask:0xf
	v_add_u32_dpp v179, v179, v179 row_bcast:31 row_mask:0xc bank_mask:0xf
	s_nop 1
	s_nop 0
	v_readlane_b32 s13, v164, 63
	v_sub_u32_e32 v164, v164, v160
	v_sub_u32_e32 v165, v165, v161
	s_nop 0
	v_add_u32_e32 v165, s13, v165
	s_nop 0
	v_readlane_b32 s13, v178, 63
	v_sub_u32_e32 v178, v178, v174
	v_sub_u32_e32 v179, v179, v175
	s_nop 0
	v_add_u32_e32 v179, s13, v179
	ds_write_b32 v144, v164 offset:0
	ds_write_b32 v144, v165 offset:256
	ds_write_b32 v144, v178 offset:7168
	ds_write_b32 v144, v179 offset:7424
	ds_read_b32 v160, v156
	ds_read_b32 v161, v157
	ds_read_b32 v174, v170
	ds_read_b32 v175, v171
	s_waitcnt lgkmcnt(0)
	v_add_u32_e32 v160, v160, v158
	v_add_u32_e32 v161, v161, v159
	v_lshl_add_u32 v160, v160, 2, s19
	v_lshl_add_u32 v161, v161, 2, s19
	v_add_u32_e32 v174, v174, v172
	v_add_u32_e32 v175, v175, v173
	v_lshl_add_u32 v174, v174, 2, s19
	v_lshl_add_u32 v175, v175, 2, s19
	ds_write_b32 v160, v166 offset:0
	ds_write_b32 v160, v168 offset:16384
	ds_write_b32 v161, v167 offset:0
	ds_write_b32 v161, v169 offset:16384
	ds_write_b32 v174, v180 offset:512
	ds_write_b32 v174, v182 offset:16896
	ds_write_b32 v175, v181 offset:512
	ds_write_b32 v175, v183 offset:16896
	ds_read_b32 v128, v147 offset:0
	ds_read_b32 v129, v147 offset:32
	ds_read_b32 v130, v147 offset:512
	ds_read_b32 v131, v147 offset:544
	s_waitcnt lgkmcnt(0)
	v_lshlrev_b32_e32 v128, 10, v128
	v_lshlrev_b32_e32 v129, 10, v129
	v_lshlrev_b32_e32 v130, 10, v130
	v_lshlrev_b32_e32 v131, 10, v131
	ds_read_b32 v166, v237 offset:1024
	ds_read_b32 v167, v237 offset:1280
	ds_read_b32 v168, v237 offset:17408
	ds_read_b32 v169, v237 offset:17664
	ds_write_b32 v144, v145 offset:0
	ds_write_b32 v144, v145 offset:256
	ds_read_b32 v180, v237 offset:1536
	ds_read_b32 v181, v237 offset:1792
	ds_read_b32 v182, v237 offset:17920
	ds_read_b32 v183, v237 offset:18176
	ds_write_b32 v144, v145 offset:7168
	ds_write_b32 v144, v145 offset:7424
	s_waitcnt lgkmcnt(0)
	v_lshrrev_b32_e32 v156, 5, v166
	v_and_b32_e32 v156, 0x1fc, v156
	v_add_u32_e32 v156, s18, v156
	v_lshrrev_b32_e32 v157, 5, v167
	v_and_b32_e32 v157, 0x1fc, v157
	v_add_u32_e32 v157, s18, v157
	v_lshrrev_b32_e32 v170, 5, v180
	v_and_b32_e32 v170, 0x1fc, v170
	v_add_u32_e32 v170, s18, v170
	v_add_u32_e32 v170, 7168, v170
	v_lshrrev_b32_e32 v171, 5, v181
	v_and_b32_e32 v171, 0x1fc, v171
	v_add_u32_e32 v171, s18, v171
	v_add_u32_e32 v171, 7168, v171
	ds_add_rtn_u32 v158, v156, v146
	ds_add_rtn_u32 v159, v157, v146
	ds_add_rtn_u32 v172, v170, v146
	ds_add_rtn_u32 v173, v171, v146
	ds_read_b32 v160, v144 offset:0
	ds_read_b32 v161, v144 offset:256
	ds_read_b32 v174, v144 offset:7168
	ds_read_b32 v175, v144 offset:7424
	s_waitcnt lgkmcnt(0)
; template <bool STORE>
; DI void peer_item(const Params& p, int item, char* smem) {
;     ...
;     for (int k = 0; k < 128; k += 8) {
;       u32x4 uq[8];
;       const int emine = e_s[tl * 128 + k + (lane >> 3)];
;       const float gmine = g_s[tl * 128 + k + (lane >> 3)];
;       const float su = SU[emine], sv = SV[emine];
; #pragma unroll
;       for (int u = 0; u < 8; ++u) {
;         int e = e_s[tl * 128 + k + u];
;         uq[u] = *(const u32x4*)(U8 + (size_t)e * 1024 + lane * 16);
	v_mov_b32_e32 v164, v160
	v_mov_b32_e32 v165, v161
	v_mov_b32_e32 v178, v174
	v_mov_b32_e32 v179, v175
	s_nop 1
	v_add_u32_dpp v164, v164, v164 row_shr:1 row_mask:0xf bank_mask:0xf bound_ctrl:0
	v_add_u32_dpp v165, v165, v165 row_shr:1 row_mask:0xf bank_mask:0xf bound_ctrl:0
	v_add_u32_dpp v178, v178, v178 row_shr:1 row_mask:0xf bank_mask:0xf bound_ctrl:0
	v_add_u32_dpp v179, v179, v179 row_shr:1 row_mask:0xf bank_mask:0xf bound_ctrl:0
	v_add_u32_dpp v164, v164, v164 row_shr:2 row_mask:0xf bank_mask:0xf bound_ctrl:0
	v_add_u32_dpp v165, v165, v165 row_shr:2 row_mask:0xf bank_mask:0xf bound_ctrl:0
	v_add_u32_dpp v178, v178, v178 row_shr:2 row_mask:0xf bank_mask:0xf bound_ctrl:0
	v_add_u32_dpp v179, v179, v179 row_shr:2 row_mask:0xf bank_mask:0xf bound_ctrl:0
	v_add_u32_dpp v164, v164, v164 row_shr:4 row_mask:0xf bank_mask:0xf bound_ctrl:0
	v_add_u32_dpp v165, v165, v165 row_shr:4 row_mask:0xf bank_mask:0xf bound_ctrl:0
	v_add_u32_dpp v178, v178, v178 row_shr:4 row_mask:0xf bank_mask:0xf bound_ctrl:0
	v_add_u32_dpp v179, v179, v179 row_shr:4 row_mask:0xf bank_mask:0xf bound_ctrl:0
	v_add_u32_dpp v164, v164, v164 row_shr:8 row_mask:0xf bank_mask:0xf bound_ctrl:0
	v_add_u32_dpp v165, v165, v165 row_shr:8 row_mask:0xf bank_mask:0xf bound_ctrl:0
	v_add_u32_dpp v178, v178, v178 row_shr:8 row_mask:0xf bank_mask:0xf bound_ctrl:0
	v_add_u32_dpp v179, v179, v179 row_shr:8 row_mask:0xf bank_mask:0xf bound_ctrl:0
	v_add_u32_dpp v164, v164, v164 row_bcast:15 row_mask:0xa bank_mask:0xf
	v_add_u32_dpp v165, v165, v165 row_bcast:15 row_mask:0xa bank_mask:0xf
	v_add_u32_dpp v178, v178, v178 row_bcast:15 row_mask:0xa bank_mask:0xf
	v_add_u32_dpp v179, v179, v179 row_bcast:15 row_mask:0xa bank_mask:0xf
	v_add_u32_dpp v164, v164, v164 row_bcast:31 row_mask:0xc bank_mask:0xf
	v_add_u32_dpp v165, v165, v165 row_bcast:31 row_mask:0xc bank_mask:0xf
	v_add_u32_dpp v178, v178, v178 row_bcast:31 row_mask:0xc bank_mask:0xf
	v_add_u32_dpp v179, v179, v179 row_bcast:31 row_mask:0xc bank_mask:0xf
	s_nop 1
	s_nop 0
	v_readlane_b32 s13, v164, 63
	v_sub_u32_e32 v164, v164, v160
	v_sub_u32_e32 v165, v165, v161
	s_nop 0
	v_add_u32_e32 v165, s13, v165
	s_nop 0
	v_readlane_b32 s13, v178, 63
	v_sub_u32_e32 v178, v178, v174
	v_sub_u32_e32 v179, v179, v175
	s_nop 0
	v_add_u32_e32 v179, s13, v179
	ds_write_b32 v144, v164 offset:0
	ds_write_b32 v144, v165 offset:256
	ds_write_b32 v144, v178 offset:7168
	ds_write_b32 v144, v179 offset:7424
	ds_read_b32 v160, v156
	ds_read_b32 v161, v157
	ds_read_b32 v174, v170
	ds_read_b32 v175, v171
	s_waitcnt lgkmcnt(0)
	v_add_u32_e32 v160, v160, v158
	v_add_u32_e32 v161, v161, v159
	v_lshl_add_u32 v160, v160, 2, s19
	v_lshl_add_u32 v161, v161, 2, s19
	v_add_u32_e32 v174, v174, v172
	v_add_u32_e32 v175, v175, v173
	v_lshl_add_u32 v174, v174, 2, s19
	v_lshl_add_u32 v175, v175, 2, s19
	ds_write_b32 v160, v166 offset:1024
	ds_write_b32 v160, v168 offset:17408
	ds_write_b32 v161, v167 offset:1024
	ds_write_b32 v161, v169 offset:17408
	ds_write_b32 v174, v180 offset:1536
	ds_write_b32 v174, v182 offset:17920
	ds_write_b32 v175, v181 offset:1536
	ds_write_b32 v175, v183 offset:17920
	ds_read_b32 v132, v147 offset:1024
	ds_read_b32 v133, v147 offset:1056
	ds_read_b32 v134, v147 offset:1536
	ds_read_b32 v135, v147 offset:1568
	s_waitcnt lgkmcnt(0)
	v_lshlrev_b32_e32 v132, 10, v132
	v_lshlrev_b32_e32 v133, 10, v133
	v_lshlrev_b32_e32 v134, 10, v134
	v_lshlrev_b32_e32 v135, 10, v135
	ds_read_b32 v166, v237 offset:2048
	ds_read_b32 v167, v237 offset:2304
	ds_read_b32 v168, v237 offset:18432
	ds_read_b32 v169, v237 offset:18688
	ds_write_b32 v144, v145 offset:0
	ds_write_b32 v144, v145 offset:256
	ds_read_b32 v180, v237 offset:2560
	ds_read_b32 v181, v237 offset:2816
	ds_read_b32 v182, v237 offset:18944
	ds_read_b32 v183, v237 offset:19200
	ds_write_b32 v144, v145 offset:7168
	ds_write_b32 v144, v145 offset:7424
	s_waitcnt lgkmcnt(0)
	v_lshrrev_b32_e32 v156, 5, v166
	v_and_b32_e32 v156, 0x1fc, v156
	v_add_u32_e32 v156, s18, v156
	v_lshrrev_b32_e32 v157, 5, v167
	v_and_b32_e32 v157, 0x1fc, v157
	v_add_u32_e32 v157, s18, v157
	v_lshrrev_b32_e32 v170, 5, v180
	v_and_b32_e32 v170, 0x1fc, v170
	v_add_u32_e32 v170, s18, v170
	v_add_u32_e32 v170, 7168, v170
	v_lshrrev_b32_e32 v171, 5, v181
	v_and_b32_e32 v171, 0x1fc, v171
	v_add_u32_e32 v171, s18, v171
	v_add_u32_e32 v171, 7168, v171
	ds_add_rtn_u32 v158, v156, v146
	ds_add_rtn_u32 v159, v157, v146
	ds_add_rtn_u32 v172, v170, v146
	ds_add_rtn_u32 v173, v171, v146
	ds_read_b32 v160, v144 offset:0
	ds_read_b32 v161, v144 offset:256
	ds_read_b32 v174, v144 offset:7168
	ds_read_b32 v175, v144 offset:7424
	s_waitcnt lgkmcnt(0)
; template <bool STORE>
; DI void peer_item(const Params& p, int item, char* smem) {
;     ...
;     for (int k = 0; k < 128; k += 8) {
;       u32x4 uq[8];
;       const int emine = e_s[tl * 128 + k + (lane >> 3)];
;       const float gmine = g_s[tl * 128 + k + (lane >> 3)];
;       const float su = SU[emine], sv = SV[emine];
; #pragma unroll
;       for (int u = 0; u < 8; ++u) {
;         int e = e_s[tl * 128 + k + u];
;         uq[u] = *(const u32x4*)(U8 + (size_t)e * 1024 + lane * 16);
	v_mov_b32_e32 v164, v160
	v_mov_b32_e32 v165, v161
	v_mov_b32_e32 v178, v174
	v_mov_b32_e32 v179, v175
	s_nop 1
	v_add_u32_dpp v164, v164, v164 row_shr:1 row_mask:0xf bank_mask:0xf bound_ctrl:0
	v_add_u32_dpp v165, v165, v165 row_shr:1 row_mask:0xf bank_mask:0xf bound_ctrl:0
	v_add_u32_dpp v178, v178, v178 row_shr:1 row_mask:0xf bank_mask:0xf bound_ctrl:0
	v_add_u32_dpp v179, v179, v179 row_shr:1 row_mask:0xf bank_mask:0xf bound_ctrl:0
	v_add_u32_dpp v164, v164, v164 row_shr:2 row_mask:0xf bank_mask:0xf bound_ctrl:0
	v_add_u32_dpp v165, v165, v165 row_shr:2 row_mask:0xf bank_mask:0xf bound_ctrl:0
	v_add_u32_dpp v178, v178, v178 row_shr:2 row_mask:0xf bank_mask:0xf bound_ctrl:0
	v_add_u32_dpp v179, v179, v179 row_shr:2 row_mask:0xf bank_mask:0xf bound_ctrl:0
	v_add_u32_dpp v164, v164, v164 row_shr:4 row_mask:0xf bank_mask:0xf bound_ctrl:0
	v_add_u32_dpp v165, v165, v165 row_shr:4 row_mask:0xf bank_mask:0xf bound_ctrl:0
	v_add_u32_dpp v178, v178, v178 row_shr:4 row_mask:0xf bank_mask:0xf bound_ctrl:0
	v_add_u32_dpp v179, v179, v179 row_shr:4 row_mask:0xf bank_mask:0xf bound_ctrl:0
	v_add_u32_dpp v164, v164, v164 row_shr:8 row_mask:0xf bank_mask:0xf bound_ctrl:0
	v_add_u32_dpp v165, v165, v165 row_shr:8 row_mask:0xf bank_mask:0xf bound_ctrl:0
	v_add_u32_dpp v178, v178, v178 row_shr:8 row_mask:0xf bank_mask:0xf bound_ctrl:0
	v_add_u32_dpp v179, v179, v179 row_shr:8 row_mask:0xf bank_mask:0xf bound_ctrl:0
	v_add_u32_dpp v164, v164, v164 row_bcast:15 row_mask:0xa bank_mask:0xf
	v_add_u32_dpp v165, v165, v165 row_bcast:15 row_mask:0xa bank_mask:0xf
	v_add_u32_dpp v178, v178, v178 row_bcast:15 row_mask:0xa bank_mask:0xf
	v_add_u32_dpp v179, v179, v179 row_bcast:15 row_mask:0xa bank_mask:0xf
	v_add_u32_dpp v164, v164, v164 row_bcast:31 row_mask:0xc bank_mask:0xf
	v_add_u32_dpp v165, v165, v165 row_bcast:31 row_mask:0xc bank_mask:0xf
	v_add_u32_dpp v178, v178, v178 row_bcast:31 row_mask:0xc bank_mask:0xf
	v_add_u32_dpp v179, v179, v179 row_bcast:31 row_mask:0xc bank_mask:0xf
	s_nop 1
	s_nop 0
	v_readlane_b32 s13, v164, 63
	v_sub_u32_e32 v164, v164, v160
	v_sub_u32_e32 v165, v165, v161
	s_nop 0
	v_add_u32_e32 v165, s13, v165
	s_nop 0
	v_readlane_b32 s13, v178, 63
	v_sub_u32_e32 v178, v178, v174
	v_sub_u32_e32 v179, v179, v175
	s_nop 0
	v_add_u32_e32 v179, s13, v179
	ds_write_b32 v144, v164 offset:0
	ds_write_b32 v144, v165 offset:256
	ds_write_b32 v144, v178 offset:7168
	ds_write_b32 v144, v179 offset:7424
	ds_read_b32 v160, v156
	ds_read_b32 v161, v157
	ds_read_b32 v174, v170
	ds_read_b32 v175, v171
	s_waitcnt lgkmcnt(0)
	v_add_u32_e32 v160, v160, v158
	v_add_u32_e32 v161, v161, v159
	v_lshl_add_u32 v160, v160, 2, s19
	v_lshl_add_u32 v161, v161, 2, s19
	v_add_u32_e32 v174, v174, v172
	v_add_u32_e32 v175, v175, v173
	v_lshl_add_u32 v174, v174, 2, s19
	v_lshl_add_u32 v175, v175, 2, s19
	ds_write_b32 v160, v166 offset:2048
	ds_write_b32 v160, v168 offset:18432
	ds_write_b32 v161, v167 offset:2048
	ds_write_b32 v161, v169 offset:18432
	ds_write_b32 v174, v180 offset:2560
	ds_write_b32 v174, v182 offset:18944
	ds_write_b32 v175, v181 offset:2560
	ds_write_b32 v175, v183 offset:18944
	ds_read_b32 v136, v147 offset:2048
	ds_read_b32 v137, v147 offset:2080
	ds_read_b32 v138, v147 offset:2560
	ds_read_b32 v139, v147 offset:2592
	s_waitcnt lgkmcnt(0)
	v_lshlrev_b32_e32 v136, 10, v136
	v_lshlrev_b32_e32 v137, 10, v137
	v_lshlrev_b32_e32 v138, 10, v138
	v_lshlrev_b32_e32 v139, 10, v139
	ds_read_b32 v166, v237 offset:3072
	ds_read_b32 v167, v237 offset:3328
	ds_read_b32 v168, v237 offset:19456
	ds_read_b32 v169, v237 offset:19712
	ds_write_b32 v144, v145 offset:0
	ds_write_b32 v144, v145 offset:256
	ds_read_b32 v180, v237 offset:3584
	ds_read_b32 v181, v237 offset:3840
	ds_read_b32 v182, v237 offset:19968
	ds_read_b32 v183, v237 offset:20224
	ds_write_b32 v144, v145 offset:7168
	ds_write_b32 v144, v145 offset:7424
	s_waitcnt lgkmcnt(0)
	v_lshrrev_b32_e32 v156, 5, v166
	v_and_b32_e32 v156, 0x1fc, v156
	v_add_u32_e32 v156, s18, v156
	v_lshrrev_b32_e32 v157, 5, v167
	v_and_b32_e32 v157, 0x1fc, v157
	v_add_u32_e32 v157, s18, v157
	v_lshrrev_b32_e32 v170, 5, v180
	v_and_b32_e32 v170, 0x1fc, v170
	v_add_u32_e32 v170, s18, v170
	v_add_u32_e32 v170, 7168, v170
	v_lshrrev_b32_e32 v171, 5, v181
	v_and_b32_e32 v171, 0x1fc, v171
	v_add_u32_e32 v171, s18, v171
	v_add_u32_e32 v171, 7168, v171
	ds_add_rtn_u32 v158, v156, v146
	ds_add_rtn_u32 v159, v157, v146
	ds_add_rtn_u32 v172, v170, v146
	ds_add_rtn_u32 v173, v171, v146
	ds_read_b32 v160, v144 offset:0
	ds_read_b32 v161, v144 offset:256
	ds_read_b32 v174, v144 offset:7168
	ds_read_b32 v175, v144 offset:7424
	s_waitcnt lgkmcnt(0)
; template <bool STORE>
; DI void peer_item(const Params& p, int item, char* smem) {
;     ...
;     for (int k = 0; k < 128; k += 8) {
;       u32x4 uq[8];
;       const int emine = e_s[tl * 128 + k + (lane >> 3)];
;       const float gmine = g_s[tl * 128 + k + (lane >> 3)];
;       const float su = SU[emine], sv = SV[emine];
; #pragma unroll
;       for (int u = 0; u < 8; ++u) {
;         int e = e_s[tl * 128 + k + u];
;         uq[u] = *(const u32x4*)(U8 + (size_t)e * 1024 + lane * 16);
	v_mov_b32_e32 v164, v160
	v_mov_b32_e32 v165, v161
	v_mov_b32_e32 v178, v174
	v_mov_b32_e32 v179, v175
	s_nop 1
	v_add_u32_dpp v164, v164, v164 row_shr:1 row_mask:0xf bank_mask:0xf bound_ctrl:0
	v_add_u32_dpp v165, v165, v165 row_shr:1 row_mask:0xf bank_mask:0xf bound_ctrl:0
	v_add_u32_dpp v178, v178, v178 row_shr:1 row_mask:0xf bank_mask:0xf bound_ctrl:0
	v_add_u32_dpp v179, v179, v179 row_shr:1 row_mask:0xf bank_mask:0xf bound_ctrl:0
	v_add_u32_dpp v164, v164, v164 row_shr:2 row_mask:0xf bank_mask:0xf bound_ctrl:0
	v_add_u32_dpp v165, v165, v165 row_shr:2 row_mask:0xf bank_mask:0xf bound_ctrl:0
	v_add_u32_dpp v178, v178, v178 row_shr:2 row_mask:0xf bank_mask:0xf bound_ctrl:0
	v_add_u32_dpp v179, v179, v179 row_shr:2 row_mask:0xf bank_mask:0xf bound_ctrl:0
	v_add_u32_dpp v164, v164, v164 row_shr:4 row_mask:0xf bank_mask:0xf bound_ctrl:0
	v_add_u32_dpp v165, v165, v165 row_shr:4 row_mask:0xf bank_mask:0xf bound_ctrl:0
	v_add_u32_dpp v178, v178, v178 row_shr:4 row_mask:0xf bank_mask:0xf bound_ctrl:0
	v_add_u32_dpp v179, v179, v179 row_shr:4 row_mask:0xf bank_mask:0xf bound_ctrl:0
	v_add_u32_dpp v164, v164, v164 row_shr:8 row_mask:0xf bank_mask:0xf bound_ctrl:0
	v_add_u32_dpp v165, v165, v165 row_shr:8 row_mask:0xf bank_mask:0xf bound_ctrl:0
	v_add_u32_dpp v178, v178, v178 row_shr:8 row_mask:0xf bank_mask:0xf bound_ctrl:0
	v_add_u32_dpp v179, v179, v179 row_shr:8 row_mask:0xf bank_mask:0xf bound_ctrl:0
	v_add_u32_dpp v164, v164, v164 row_bcast:15 row_mask:0xa bank_mask:0xf
	v_add_u32_dpp v165, v165, v165 row_bcast:15 row_mask:0xa bank_mask:0xf
	v_add_u32_dpp v178, v178, v178 row_bcast:15 row_mask:0xa bank_mask:0xf
	v_add_u32_dpp v179, v179, v179 row_bcast:15 row_mask:0xa bank_mask:0xf
	v_add_u32_dpp v164, v164, v164 row_bcast:31 row_mask:0xc bank_mask:0xf
	v_add_u32_dpp v165, v165, v165 row_bcast:31 row_mask:0xc bank_mask:0xf
	v_add_u32_dpp v178, v178, v178 row_bcast:31 row_mask:0xc bank_mask:0xf
	v_add_u32_dpp v179, v179, v179 row_bcast:31 row_mask:0xc bank_mask:0xf
	s_nop 1
	s_nop 0
	v_readlane_b32 s13, v164, 63
	v_sub_u32_e32 v164, v164, v160
	v_sub_u32_e32 v165, v165, v161
	s_nop 0
	v_add_u32_e32 v165, s13, v165
	s_nop 0
	v_readlane_b32 s13, v178, 63
	v_sub_u32_e32 v178, v178, v174
	v_sub_u32_e32 v179, v179, v175
	s_nop 0
	v_add_u32_e32 v179, s13, v179
	ds_write_b32 v144, v164 offset:0
	ds_write_b32 v144, v165 offset:256
	ds_write_b32 v144, v178 offset:7168
	ds_write_b32 v144, v179 offset:7424
	ds_read_b32 v160, v156
	ds_read_b32 v161, v157
	ds_read_b32 v174, v170
	ds_read_b32 v175, v171
	s_waitcnt lgkmcnt(0)
	v_add_u32_e32 v160, v160, v158
	v_add_u32_e32 v161, v161, v159
	v_lshl_add_u32 v160, v160, 2, s19
	v_lshl_add_u32 v161, v161, 2, s19
	v_add_u32_e32 v174, v174, v172
	v_add_u32_e32 v175, v175, v173
	v_lshl_add_u32 v174, v174, 2, s19
	v_lshl_add_u32 v175, v175, 2, s19
	ds_write_b32 v160, v166 offset:3072
	ds_write_b32 v160, v168 offset:19456
	ds_write_b32 v161, v167 offset:3072
	ds_write_b32 v161, v169 offset:19456
	ds_write_b32 v174, v180 offset:3584
	ds_write_b32 v174, v182 offset:19968
	ds_write_b32 v175, v181 offset:3584
	ds_write_b32 v175, v183 offset:19968
	ds_read_b32 v140, v147 offset:3072
	ds_read_b32 v141, v147 offset:3104
	ds_read_b32 v142, v147 offset:3584
	ds_read_b32 v143, v147 offset:3616
	s_waitcnt lgkmcnt(0)
	v_lshlrev_b32_e32 v140, 10, v140
	v_lshlrev_b32_e32 v141, 10, v141
	v_lshlrev_b32_e32 v142, 10, v142
	v_lshlrev_b32_e32 v143, 10, v143
	s_waitcnt vmcnt(0)
; DI float bflo(unsigned u) { return __uint_as_float(u << 16); }
; DI float bfhi(unsigned u) { return __uint_as_float(u & 0xffff0000u); }
; template <bool STORE>
; DI void peer_item(const Params& p, int item, char* smem) {
;     ...
;     float xf[16];
;     {
; #pragma unroll
;       for (int i = 0; i < 4; ++i) {
;         const uint2 xv = *(const uint2*)(XN2 + tok * 1024 + 256 * i + lane * 4);
;         xf[4 * i] = bflo(xv.x); xf[4 * i + 1] = bfhi(xv.x); xf[4 * i + 2] = bflo(xv.y); xf[4 * i + 3] = bfhi(xv.y);
;       }
;     }
; #pragma unroll 2
;     for (int k = 0; k < 128; k += 8) {
;       u32x4 uq[8];
;       const int emine = e_s[tl * 128 + k + (lane >> 3)];
;       const float gmine = g_s[tl * 128 + k + (lane >> 3)];
;       const float su = SU[emine], sv = SV[emine];
; #pragma unroll
;       for (int u = 0; u < 8; ++u) {
;         int e = e_s[tl * 128 + k + u];
;         uq[u] = *(const u32x4*)(U8 + (size_t)e * 1024 + lane * 16);
	v_lshlrev_b32_e32 v0, 16, v2
	v_and_b32_e32 v1, 0xffff0000, v2
	v_lshlrev_b32_e32 v2, 16, v3
	v_and_b32_e32 v3, 0xffff0000, v3
	v_lshlrev_b32_e32 v4, 16, v6
	v_and_b32_e32 v5, 0xffff0000, v6
	v_lshlrev_b32_e32 v6, 16, v7
	v_and_b32_e32 v7, 0xffff0000, v7
	v_lshlrev_b32_e32 v8, 16, v10
	v_and_b32_e32 v9, 0xffff0000, v10
	v_lshlrev_b32_e32 v10, 16, v11
	v_and_b32_e32 v11, 0xffff0000, v11
	v_lshlrev_b32_e32 v12, 16, v14
	v_and_b32_e32 v13, 0xffff0000, v14
	v_lshlrev_b32_e32 v14, 16, v15
	v_and_b32_e32 v15, 0xffff0000, v15
	v_lshlrev_b32_e32 v16, 16, v18
	v_and_b32_e32 v17, 0xffff0000, v18
	v_lshlrev_b32_e32 v18, 16, v19
	v_and_b32_e32 v19, 0xffff0000, v19
	v_lshlrev_b32_e32 v20, 16, v22
	v_and_b32_e32 v21, 0xffff0000, v22
	v_lshlrev_b32_e32 v22, 16, v23
	v_and_b32_e32 v23, 0xffff0000, v23
	v_lshlrev_b32_e32 v24, 16, v26
	v_and_b32_e32 v25, 0xffff0000, v26
	v_lshlrev_b32_e32 v26, 16, v27
	v_and_b32_e32 v27, 0xffff0000, v27
	v_lshlrev_b32_e32 v28, 16, v30
	v_and_b32_e32 v29, 0xffff0000, v30
	v_lshlrev_b32_e32 v30, 16, v31
	v_and_b32_e32 v31, 0xffff0000, v31
	v_lshlrev_b32_e32 v32, 16, v34
	v_and_b32_e32 v33, 0xffff0000, v34
	v_lshlrev_b32_e32 v34, 16, v35
	v_and_b32_e32 v35, 0xffff0000, v35
	v_lshlrev_b32_e32 v36, 16, v38
	v_and_b32_e32 v37, 0xffff0000, v38
	v_lshlrev_b32_e32 v38, 16, v39
	v_and_b32_e32 v39, 0xffff0000, v39
	v_lshlrev_b32_e32 v40, 16, v42
	v_and_b32_e32 v41, 0xffff0000, v42
	v_lshlrev_b32_e32 v42, 16, v43
	v_and_b32_e32 v43, 0xffff0000, v43
	v_lshlrev_b32_e32 v44, 16, v46
	v_and_b32_e32 v45, 0xffff0000, v46
	v_lshlrev_b32_e32 v46, 16, v47
	v_and_b32_e32 v47, 0xffff0000, v47
	v_lshlrev_b32_e32 v48, 16, v50
	v_and_b32_e32 v49, 0xffff0000, v50
	v_lshlrev_b32_e32 v50, 16, v51
	v_and_b32_e32 v51, 0xffff0000, v51
	v_lshlrev_b32_e32 v52, 16, v54
	v_and_b32_e32 v53, 0xffff0000, v54
	v_lshlrev_b32_e32 v54, 16, v55
	v_and_b32_e32 v55, 0xffff0000, v55
	v_lshlrev_b32_e32 v56, 16, v58
	v_and_b32_e32 v57, 0xffff0000, v58
	v_lshlrev_b32_e32 v58, 16, v59
	v_and_b32_e32 v59, 0xffff0000, v59
	v_lshlrev_b32_e32 v60, 16, v62
	v_and_b32_e32 v61, 0xffff0000, v62
	v_lshlrev_b32_e32 v62, 16, v63
	v_and_b32_e32 v63, 0xffff0000, v63
	v_lshrrev_b32_e32 v235, 3, v213
	v_lshl_add_u32 v235, v235, 2, s19
	s_mov_b32 s72, 0
	s_mov_b32 s73, 1
	s_mov_b32 s74, 2
	s_mov_b32 s75, 3
	s_mov_b32 s76, 4
	s_mov_b32 s77, 5
	s_mov_b32 s78, 6
	s_mov_b32 s79, 7
	s_mov_b32 s58, 8
	s_mov_b32 s59, 9
	s_mov_b32 s60, 10
	s_mov_b32 s61, 11
	s_mov_b32 s62, 12
	s_mov_b32 s63, 13
	s_mov_b32 s64, 14
	s_mov_b32 s65, 15
	s_nop 0
	v_readlane_b32 s48, v128, s72
	v_readlane_b32 s49, v128, s73
	v_readlane_b32 s50, v128, s74
	v_readlane_b32 s51, v128, s75
	v_readlane_b32 s52, v128, s76
	v_readlane_b32 s53, v128, s77
	v_readlane_b32 s54, v128, s78
	v_readlane_b32 s55, v128, s79
	s_add_u32 s32, s0, s48
	s_addc_u32 s33, s1, 0
	s_add_u32 s34, s0, s49
	s_addc_u32 s35, s1, 0
	s_add_u32 s36, s0, s50
	s_addc_u32 s37, s1, 0
	s_add_u32 s38, s0, s51
	s_addc_u32 s39, s1, 0
	s_add_u32 s40, s0, s52
	s_addc_u32 s41, s1, 0
	s_add_u32 s42, s0, s53
	s_addc_u32 s43, s1, 0
	s_add_u32 s44, s0, s54
	s_addc_u32 s45, s1, 0
	s_add_u32 s46, s0, s55
	s_addc_u32 s47, s1, 0
	global_load_dwordx4 v[144:147], v234, s[32:33]
	global_load_dwordx4 v[148:151], v234, s[34:35]
	global_load_dwordx4 v[152:155], v234, s[36:37]
	global_load_dwordx4 v[156:159], v234, s[38:39]
	global_load_dwordx4 v[160:163], v234, s[40:41]
	global_load_dwordx4 v[164:167], v234, s[42:43]
	global_load_dwordx4 v[168:171], v234, s[44:45]
	global_load_dwordx4 v[172:175], v234, s[46:47]
	v_readlane_b32 s48, v130, s72
	v_readlane_b32 s49, v130, s73
	v_readlane_b32 s50, v130, s74
	v_readlane_b32 s51, v130, s75
	v_readlane_b32 s52, v130, s76
	v_readlane_b32 s53, v130, s77
	v_readlane_b32 s54, v130, s78
	v_readlane_b32 s55, v130, s79
	s_add_u32 s32, s0, s48
	s_addc_u32 s33, s1, 0
	s_add_u32 s34, s0, s49
	s_addc_u32 s35, s1, 0
	s_add_u32 s36, s0, s50
	s_addc_u32 s37, s1, 0
	s_add_u32 s38, s0, s51
	s_addc_u32 s39, s1, 0
	s_add_u32 s40, s0, s52
	s_addc_u32 s41, s1, 0
	s_add_u32 s42, s0, s53
	s_addc_u32 s43, s1, 0
	s_add_u32 s44, s0, s54
	s_addc_u32 s45, s1, 0
	s_add_u32 s46, s0, s55
	s_addc_u32 s47, s1, 0
	global_load_dwordx4 v[176:179], v234, s[32:33]
	global_load_dwordx4 v[180:183], v234, s[34:35]
	global_load_dwordx4 v[184:187], v234, s[36:37]
	global_load_dwordx4 v[188:191], v234, s[38:39]
	global_load_dwordx4 v[192:195], v234, s[40:41]
	global_load_dwordx4 v[196:199], v234, s[42:43]
	global_load_dwordx4 v[200:203], v234, s[44:45]
	global_load_dwordx4 v[204:207], v234, s[46:47]
	v_readlane_b32 s48, v132, s72
	v_readlane_b32 s49, v132, s73
	v_readlane_b32 s50, v132, s74
	v_readlane_b32 s51, v132, s75
	v_readlane_b32 s52, v132, s76
	v_readlane_b32 s53, v132, s77
	v_readlane_b32 s54, v132, s78
	v_readlane_b32 s55, v132, s79
	s_add_u32 s32, s0, s48
	s_addc_u32 s33, s1, 0
	s_add_u32 s34, s0, s49
	s_addc_u32 s35, s1, 0
	s_add_u32 s36, s0, s50
	s_addc_u32 s37, s1, 0
	s_add_u32 s38, s0, s51
	s_addc_u32 s39, s1, 0
	s_add_u32 s40, s0, s52
	s_addc_u32 s41, s1, 0
	s_add_u32 s42, s0, s53
	s_addc_u32 s43, s1, 0
	s_add_u32 s44, s0, s54
	s_addc_u32 s45, s1, 0
	s_add_u32 s46, s0, s55
	s_addc_u32 s47, s1, 0
	global_load_dwordx4 v[64:67], v234, s[32:33]
	global_load_dwordx4 v[68:71], v234, s[34:35]
	global_load_dwordx4 v[72:75], v234, s[36:37]
	global_load_dwordx4 v[76:79], v234, s[38:39]
	global_load_dwordx4 v[80:83], v234, s[40:41]
	global_load_dwordx4 v[84:87], v234, s[42:43]
	global_load_dwordx4 v[88:91], v234, s[44:45]
	global_load_dwordx4 v[92:95], v234, s[46:47]
	s_mov_b32 s12, 0
